# phase_p0 modulation GEMV: rolling prefetch, 24 row loads in flight instead of 4 exposed batches of 16
# baseline (speedup 1.0000x reference)
.LBB0_11:
	s_waitcnt vmcnt(0)
	s_mov_b32 s0, 0xfffb8000
	s_mov_b32 s1, -1
	s_mov_b32 s42, 0x9000
	s_mov_b32 s43, 0
	v_lshl_add_u64 v[50:51], v[24:25], 0, s[0:1]
	v_add_u32_e32 v54, 0x14000, v59
	ds_read_b128 v[156:159], v54
	ds_read_b128 v[160:163], v54 offset:4096
	ds_read_b128 v[164:167], v54 offset:8192
	ds_read_b128 v[168:171], v54 offset:12288
	ds_read_b128 v[172:175], v54 offset:16384
	global_load_dwordx4 v[60:63], v[50:51], off
	v_lshl_add_u64 v[50:51], v[50:51], 0, s[42:43]
	global_load_dwordx4 v[64:67], v[50:51], off
	v_lshl_add_u64 v[50:51], v[50:51], 0, s[42:43]
	global_load_dwordx4 v[68:71], v[50:51], off
	v_lshl_add_u64 v[50:51], v[50:51], 0, s[42:43]
	global_load_dwordx4 v[72:75], v[50:51], off
	v_lshl_add_u64 v[50:51], v[50:51], 0, s[42:43]
	global_load_dwordx4 v[76:79], v[50:51], off
	v_lshl_add_u64 v[50:51], v[50:51], 0, s[42:43]
	global_load_dwordx4 v[80:83], v[50:51], off
	v_lshl_add_u64 v[50:51], v[50:51], 0, s[42:43]
	global_load_dwordx4 v[84:87], v[50:51], off
	v_lshl_add_u64 v[50:51], v[50:51], 0, s[42:43]
	global_load_dwordx4 v[88:91], v[50:51], off
	v_lshl_add_u64 v[50:51], v[50:51], 0, s[42:43]
	global_load_dwordx4 v[92:95], v[50:51], off
	v_lshl_add_u64 v[50:51], v[50:51], 0, s[42:43]
	global_load_dwordx4 v[96:99], v[50:51], off
	v_lshl_add_u64 v[50:51], v[50:51], 0, s[42:43]
	global_load_dwordx4 v[100:103], v[50:51], off
	v_lshl_add_u64 v[50:51], v[50:51], 0, s[42:43]
	global_load_dwordx4 v[104:107], v[50:51], off
	v_lshl_add_u64 v[50:51], v[50:51], 0, s[42:43]
	global_load_dwordx4 v[108:111], v[50:51], off
	v_lshl_add_u64 v[50:51], v[50:51], 0, s[42:43]
	global_load_dwordx4 v[112:115], v[50:51], off
	v_lshl_add_u64 v[50:51], v[50:51], 0, s[42:43]
	global_load_dwordx4 v[116:119], v[50:51], off
	v_lshl_add_u64 v[50:51], v[50:51], 0, s[42:43]
	global_load_dwordx4 v[120:123], v[50:51], off
	v_lshl_add_u64 v[50:51], v[50:51], 0, s[42:43]
	global_load_dwordx4 v[124:127], v[50:51], off
	v_lshl_add_u64 v[50:51], v[50:51], 0, s[42:43]
	global_load_dwordx4 v[128:131], v[50:51], off
	v_lshl_add_u64 v[50:51], v[50:51], 0, s[42:43]
	global_load_dwordx4 v[132:135], v[50:51], off
	v_lshl_add_u64 v[50:51], v[50:51], 0, s[42:43]
	global_load_dwordx4 v[136:139], v[50:51], off
	v_lshl_add_u64 v[50:51], v[50:51], 0, s[42:43]
	global_load_dwordx4 v[140:143], v[50:51], off
	v_lshl_add_u64 v[50:51], v[50:51], 0, s[42:43]
	global_load_dwordx4 v[144:147], v[50:51], off
	v_lshl_add_u64 v[50:51], v[50:51], 0, s[42:43]
	global_load_dwordx4 v[148:151], v[50:51], off
	v_lshl_add_u64 v[50:51], v[50:51], 0, s[42:43]
	global_load_dwordx4 v[152:155], v[50:51], off
	v_lshl_add_u64 v[50:51], v[50:51], 0, s[42:43]
	ds_read_b128 v[2:5], v54 offset:16
	ds_read_b128 v[6:9], v54 offset:4112
	ds_read_b128 v[38:41], v54 offset:8208
	ds_read_b128 v[42:45], v54 offset:12304
	ds_read_b128 v[46:49], v54 offset:16400
	s_waitcnt lgkmcnt(5)
	s_waitcnt vmcnt(23)
	v_pk_fma_f32 v[16:17], v[62:63], v[156:157], v[16:17] op_sel_hi:[1,0,1]
	v_pk_fma_f32 v[20:21], v[60:61], v[156:157], v[20:21] op_sel_hi:[1,0,1]
	v_pk_fma_f32 v[18:19], v[62:63], v[160:161], v[18:19] op_sel_hi:[1,0,1]
	v_pk_fma_f32 v[28:29], v[60:61], v[160:161], v[28:29] op_sel_hi:[1,0,1]
	v_pk_fma_f32 v[22:23], v[62:63], v[164:165], v[22:23] op_sel_hi:[1,0,1]
	v_pk_fma_f32 v[32:33], v[60:61], v[164:165], v[32:33] op_sel_hi:[1,0,1]
	v_pk_fma_f32 v[26:27], v[62:63], v[168:169], v[26:27] op_sel_hi:[1,0,1]
	v_pk_fma_f32 v[34:35], v[60:61], v[168:169], v[34:35] op_sel_hi:[1,0,1]
	v_pk_fma_f32 v[30:31], v[62:63], v[172:173], v[30:31] op_sel_hi:[1,0,1]
	v_pk_fma_f32 v[36:37], v[60:61], v[172:173], v[36:37] op_sel_hi:[1,0,1]
	global_load_dwordx4 v[60:63], v[50:51], off
	v_lshl_add_u64 v[50:51], v[50:51], 0, s[42:43]
	s_waitcnt vmcnt(23)
	v_pk_fma_f32 v[16:17], v[66:67], v[156:157], v[16:17] op_sel:[0,1,0]
	v_pk_fma_f32 v[20:21], v[64:65], v[156:157], v[20:21] op_sel:[0,1,0]
	v_pk_fma_f32 v[18:19], v[66:67], v[160:161], v[18:19] op_sel:[0,1,0]
	v_pk_fma_f32 v[28:29], v[64:65], v[160:161], v[28:29] op_sel:[0,1,0]
	v_pk_fma_f32 v[22:23], v[66:67], v[164:165], v[22:23] op_sel:[0,1,0]
	v_pk_fma_f32 v[32:33], v[64:65], v[164:165], v[32:33] op_sel:[0,1,0]
	v_pk_fma_f32 v[26:27], v[66:67], v[168:169], v[26:27] op_sel:[0,1,0]
	v_pk_fma_f32 v[34:35], v[64:65], v[168:169], v[34:35] op_sel:[0,1,0]
	v_pk_fma_f32 v[30:31], v[66:67], v[172:173], v[30:31] op_sel:[0,1,0]
	v_pk_fma_f32 v[36:37], v[64:65], v[172:173], v[36:37] op_sel:[0,1,0]
	global_load_dwordx4 v[64:67], v[50:51], off
	v_lshl_add_u64 v[50:51], v[50:51], 0, s[42:43]
	s_waitcnt vmcnt(23)
	v_pk_fma_f32 v[16:17], v[70:71], v[158:159], v[16:17] op_sel_hi:[1,0,1]
	v_pk_fma_f32 v[20:21], v[68:69], v[158:159], v[20:21] op_sel_hi:[1,0,1]
	v_pk_fma_f32 v[18:19], v[70:71], v[162:163], v[18:19] op_sel_hi:[1,0,1]
	v_pk_fma_f32 v[28:29], v[68:69], v[162:163], v[28:29] op_sel_hi:[1,0,1]
	v_pk_fma_f32 v[22:23], v[70:71], v[166:167], v[22:23] op_sel_hi:[1,0,1]
	v_pk_fma_f32 v[32:33], v[68:69], v[166:167], v[32:33] op_sel_hi:[1,0,1]
	v_pk_fma_f32 v[26:27], v[70:71], v[170:171], v[26:27] op_sel_hi:[1,0,1]
	v_pk_fma_f32 v[34:35], v[68:69], v[170:171], v[34:35] op_sel_hi:[1,0,1]
	v_pk_fma_f32 v[30:31], v[70:71], v[174:175], v[30:31] op_sel_hi:[1,0,1]
	v_pk_fma_f32 v[36:37], v[68:69], v[174:175], v[36:37] op_sel_hi:[1,0,1]
	global_load_dwordx4 v[68:71], v[50:51], off
	v_lshl_add_u64 v[50:51], v[50:51], 0, s[42:43]
	s_waitcnt vmcnt(23)
	v_pk_fma_f32 v[16:17], v[74:75], v[158:159], v[16:17] op_sel:[0,1,0]
	v_pk_fma_f32 v[20:21], v[72:73], v[158:159], v[20:21] op_sel:[0,1,0]
	v_pk_fma_f32 v[18:19], v[74:75], v[162:163], v[18:19] op_sel:[0,1,0]
	v_pk_fma_f32 v[28:29], v[72:73], v[162:163], v[28:29] op_sel:[0,1,0]
	v_pk_fma_f32 v[22:23], v[74:75], v[166:167], v[22:23] op_sel:[0,1,0]
	v_pk_fma_f32 v[32:33], v[72:73], v[166:167], v[32:33] op_sel:[0,1,0]
	v_pk_fma_f32 v[26:27], v[74:75], v[170:171], v[26:27] op_sel:[0,1,0]
	v_pk_fma_f32 v[34:35], v[72:73], v[170:171], v[34:35] op_sel:[0,1,0]
	v_pk_fma_f32 v[30:31], v[74:75], v[174:175], v[30:31] op_sel:[0,1,0]
	v_pk_fma_f32 v[36:37], v[72:73], v[174:175], v[36:37] op_sel:[0,1,0]
	global_load_dwordx4 v[72:75], v[50:51], off
	v_lshl_add_u64 v[50:51], v[50:51], 0, s[42:43]
	ds_read_b128 v[156:159], v54 offset:32
	ds_read_b128 v[160:163], v54 offset:4128
	ds_read_b128 v[164:167], v54 offset:8224
	ds_read_b128 v[168:171], v54 offset:12320
	ds_read_b128 v[172:175], v54 offset:16416
	s_waitcnt lgkmcnt(5)
	s_waitcnt vmcnt(23)
	v_pk_fma_f32 v[16:17], v[78:79], v[2:3], v[16:17] op_sel_hi:[1,0,1]
	v_pk_fma_f32 v[20:21], v[76:77], v[2:3], v[20:21] op_sel_hi:[1,0,1]
	v_pk_fma_f32 v[18:19], v[78:79], v[6:7], v[18:19] op_sel_hi:[1,0,1]
	v_pk_fma_f32 v[28:29], v[76:77], v[6:7], v[28:29] op_sel_hi:[1,0,1]
	v_pk_fma_f32 v[22:23], v[78:79], v[38:39], v[22:23] op_sel_hi:[1,0,1]
	v_pk_fma_f32 v[32:33], v[76:77], v[38:39], v[32:33] op_sel_hi:[1,0,1]
	v_pk_fma_f32 v[26:27], v[78:79], v[42:43], v[26:27] op_sel_hi:[1,0,1]
	v_pk_fma_f32 v[34:35], v[76:77], v[42:43], v[34:35] op_sel_hi:[1,0,1]
	v_pk_fma_f32 v[30:31], v[78:79], v[46:47], v[30:31] op_sel_hi:[1,0,1]
	v_pk_fma_f32 v[36:37], v[76:77], v[46:47], v[36:37] op_sel_hi:[1,0,1]
	global_load_dwordx4 v[76:79], v[50:51], off
	v_lshl_add_u64 v[50:51], v[50:51], 0, s[42:43]
	s_waitcnt vmcnt(23)
	v_pk_fma_f32 v[16:17], v[82:83], v[2:3], v[16:17] op_sel:[0,1,0]
	v_pk_fma_f32 v[20:21], v[80:81], v[2:3], v[20:21] op_sel:[0,1,0]
	v_pk_fma_f32 v[18:19], v[82:83], v[6:7], v[18:19] op_sel:[0,1,0]
	v_pk_fma_f32 v[28:29], v[80:81], v[6:7], v[28:29] op_sel:[0,1,0]
	v_pk_fma_f32 v[22:23], v[82:83], v[38:39], v[22:23] op_sel:[0,1,0]
	v_pk_fma_f32 v[32:33], v[80:81], v[38:39], v[32:33] op_sel:[0,1,0]
	v_pk_fma_f32 v[26:27], v[82:83], v[42:43], v[26:27] op_sel:[0,1,0]
	v_pk_fma_f32 v[34:35], v[80:81], v[42:43], v[34:35] op_sel:[0,1,0]
	v_pk_fma_f32 v[30:31], v[82:83], v[46:47], v[30:31] op_sel:[0,1,0]
	v_pk_fma_f32 v[36:37], v[80:81], v[46:47], v[36:37] op_sel:[0,1,0]
	global_load_dwordx4 v[80:83], v[50:51], off
	v_lshl_add_u64 v[50:51], v[50:51], 0, s[42:43]
	s_waitcnt vmcnt(23)
	v_pk_fma_f32 v[16:17], v[86:87], v[4:5], v[16:17] op_sel_hi:[1,0,1]
	v_pk_fma_f32 v[20:21], v[84:85], v[4:5], v[20:21] op_sel_hi:[1,0,1]
	v_pk_fma_f32 v[18:19], v[86:87], v[8:9], v[18:19] op_sel_hi:[1,0,1]
	v_pk_fma_f32 v[28:29], v[84:85], v[8:9], v[28:29] op_sel_hi:[1,0,1]
	v_pk_fma_f32 v[22:23], v[86:87], v[40:41], v[22:23] op_sel_hi:[1,0,1]
	v_pk_fma_f32 v[32:33], v[84:85], v[40:41], v[32:33] op_sel_hi:[1,0,1]
	v_pk_fma_f32 v[26:27], v[86:87], v[44:45], v[26:27] op_sel_hi:[1,0,1]
	v_pk_fma_f32 v[34:35], v[84:85], v[44:45], v[34:35] op_sel_hi:[1,0,1]
	v_pk_fma_f32 v[30:31], v[86:87], v[48:49], v[30:31] op_sel_hi:[1,0,1]
	v_pk_fma_f32 v[36:37], v[84:85], v[48:49], v[36:37] op_sel_hi:[1,0,1]
	global_load_dwordx4 v[84:87], v[50:51], off
	v_lshl_add_u64 v[50:51], v[50:51], 0, s[42:43]
	s_waitcnt vmcnt(23)
	v_pk_fma_f32 v[16:17], v[90:91], v[4:5], v[16:17] op_sel:[0,1,0]
	v_pk_fma_f32 v[20:21], v[88:89], v[4:5], v[20:21] op_sel:[0,1,0]
	v_pk_fma_f32 v[18:19], v[90:91], v[8:9], v[18:19] op_sel:[0,1,0]
	v_pk_fma_f32 v[28:29], v[88:89], v[8:9], v[28:29] op_sel:[0,1,0]
	v_pk_fma_f32 v[22:23], v[90:91], v[40:41], v[22:23] op_sel:[0,1,0]
	v_pk_fma_f32 v[32:33], v[88:89], v[40:41], v[32:33] op_sel:[0,1,0]
	v_pk_fma_f32 v[26:27], v[90:91], v[44:45], v[26:27] op_sel:[0,1,0]
	v_pk_fma_f32 v[34:35], v[88:89], v[44:45], v[34:35] op_sel:[0,1,0]
	v_pk_fma_f32 v[30:31], v[90:91], v[48:49], v[30:31] op_sel:[0,1,0]
	v_pk_fma_f32 v[36:37], v[88:89], v[48:49], v[36:37] op_sel:[0,1,0]
	global_load_dwordx4 v[88:91], v[50:51], off
	v_lshl_add_u64 v[50:51], v[50:51], 0, s[42:43]
	ds_read_b128 v[2:5], v54 offset:48
	ds_read_b128 v[6:9], v54 offset:4144
	ds_read_b128 v[38:41], v54 offset:8240
	ds_read_b128 v[42:45], v54 offset:12336
	ds_read_b128 v[46:49], v54 offset:16432
	s_waitcnt lgkmcnt(5)
	s_waitcnt vmcnt(23)
	v_pk_fma_f32 v[16:17], v[94:95], v[156:157], v[16:17] op_sel_hi:[1,0,1]
	v_pk_fma_f32 v[20:21], v[92:93], v[156:157], v[20:21] op_sel_hi:[1,0,1]
	v_pk_fma_f32 v[18:19], v[94:95], v[160:161], v[18:19] op_sel_hi:[1,0,1]
	v_pk_fma_f32 v[28:29], v[92:93], v[160:161], v[28:29] op_sel_hi:[1,0,1]
	v_pk_fma_f32 v[22:23], v[94:95], v[164:165], v[22:23] op_sel_hi:[1,0,1]
	v_pk_fma_f32 v[32:33], v[92:93], v[164:165], v[32:33] op_sel_hi:[1,0,1]
	v_pk_fma_f32 v[26:27], v[94:95], v[168:169], v[26:27] op_sel_hi:[1,0,1]
	v_pk_fma_f32 v[34:35], v[92:93], v[168:169], v[34:35] op_sel_hi:[1,0,1]
	v_pk_fma_f32 v[30:31], v[94:95], v[172:173], v[30:31] op_sel_hi:[1,0,1]
	v_pk_fma_f32 v[36:37], v[92:93], v[172:173], v[36:37] op_sel_hi:[1,0,1]
	global_load_dwordx4 v[92:95], v[50:51], off
	v_lshl_add_u64 v[50:51], v[50:51], 0, s[42:43]
	s_waitcnt vmcnt(23)
	v_pk_fma_f32 v[16:17], v[98:99], v[156:157], v[16:17] op_sel:[0,1,0]
	v_pk_fma_f32 v[20:21], v[96:97], v[156:157], v[20:21] op_sel:[0,1,0]
	v_pk_fma_f32 v[18:19], v[98:99], v[160:161], v[18:19] op_sel:[0,1,0]
	v_pk_fma_f32 v[28:29], v[96:97], v[160:161], v[28:29] op_sel:[0,1,0]
	v_pk_fma_f32 v[22:23], v[98:99], v[164:165], v[22:23] op_sel:[0,1,0]
	v_pk_fma_f32 v[32:33], v[96:97], v[164:165], v[32:33] op_sel:[0,1,0]
	v_pk_fma_f32 v[26:27], v[98:99], v[168:169], v[26:27] op_sel:[0,1,0]
	v_pk_fma_f32 v[34:35], v[96:97], v[168:169], v[34:35] op_sel:[0,1,0]
	v_pk_fma_f32 v[30:31], v[98:99], v[172:173], v[30:31] op_sel:[0,1,0]
	v_pk_fma_f32 v[36:37], v[96:97], v[172:173], v[36:37] op_sel:[0,1,0]
	global_load_dwordx4 v[96:99], v[50:51], off
	v_lshl_add_u64 v[50:51], v[50:51], 0, s[42:43]
	s_waitcnt vmcnt(23)
	v_pk_fma_f32 v[16:17], v[102:103], v[158:159], v[16:17] op_sel_hi:[1,0,1]
	v_pk_fma_f32 v[20:21], v[100:101], v[158:159], v[20:21] op_sel_hi:[1,0,1]
	v_pk_fma_f32 v[18:19], v[102:103], v[162:163], v[18:19] op_sel_hi:[1,0,1]
	v_pk_fma_f32 v[28:29], v[100:101], v[162:163], v[28:29] op_sel_hi:[1,0,1]
	v_pk_fma_f32 v[22:23], v[102:103], v[166:167], v[22:23] op_sel_hi:[1,0,1]
	v_pk_fma_f32 v[32:33], v[100:101], v[166:167], v[32:33] op_sel_hi:[1,0,1]
	v_pk_fma_f32 v[26:27], v[102:103], v[170:171], v[26:27] op_sel_hi:[1,0,1]
	v_pk_fma_f32 v[34:35], v[100:101], v[170:171], v[34:35] op_sel_hi:[1,0,1]
	v_pk_fma_f32 v[30:31], v[102:103], v[174:175], v[30:31] op_sel_hi:[1,0,1]
	v_pk_fma_f32 v[36:37], v[100:101], v[174:175], v[36:37] op_sel_hi:[1,0,1]
	global_load_dwordx4 v[100:103], v[50:51], off
	v_lshl_add_u64 v[50:51], v[50:51], 0, s[42:43]
	s_waitcnt vmcnt(23)
	v_pk_fma_f32 v[16:17], v[106:107], v[158:159], v[16:17] op_sel:[0,1,0]
	v_pk_fma_f32 v[20:21], v[104:105], v[158:159], v[20:21] op_sel:[0,1,0]
	v_pk_fma_f32 v[18:19], v[106:107], v[162:163], v[18:19] op_sel:[0,1,0]
	v_pk_fma_f32 v[28:29], v[104:105], v[162:163], v[28:29] op_sel:[0,1,0]
	v_pk_fma_f32 v[22:23], v[106:107], v[166:167], v[22:23] op_sel:[0,1,0]
	v_pk_fma_f32 v[32:33], v[104:105], v[166:167], v[32:33] op_sel:[0,1,0]
	v_pk_fma_f32 v[26:27], v[106:107], v[170:171], v[26:27] op_sel:[0,1,0]
	v_pk_fma_f32 v[34:35], v[104:105], v[170:171], v[34:35] op_sel:[0,1,0]
	v_pk_fma_f32 v[30:31], v[106:107], v[174:175], v[30:31] op_sel:[0,1,0]
	v_pk_fma_f32 v[36:37], v[104:105], v[174:175], v[36:37] op_sel:[0,1,0]
	global_load_dwordx4 v[104:107], v[50:51], off
	v_lshl_add_u64 v[50:51], v[50:51], 0, s[42:43]
	ds_read_b128 v[156:159], v54 offset:64
	ds_read_b128 v[160:163], v54 offset:4160
	ds_read_b128 v[164:167], v54 offset:8256
	ds_read_b128 v[168:171], v54 offset:12352
	ds_read_b128 v[172:175], v54 offset:16448
	s_waitcnt lgkmcnt(5)
	s_waitcnt vmcnt(23)
	v_pk_fma_f32 v[16:17], v[110:111], v[2:3], v[16:17] op_sel_hi:[1,0,1]
	v_pk_fma_f32 v[20:21], v[108:109], v[2:3], v[20:21] op_sel_hi:[1,0,1]
	v_pk_fma_f32 v[18:19], v[110:111], v[6:7], v[18:19] op_sel_hi:[1,0,1]
	v_pk_fma_f32 v[28:29], v[108:109], v[6:7], v[28:29] op_sel_hi:[1,0,1]
	v_pk_fma_f32 v[22:23], v[110:111], v[38:39], v[22:23] op_sel_hi:[1,0,1]
	v_pk_fma_f32 v[32:33], v[108:109], v[38:39], v[32:33] op_sel_hi:[1,0,1]
	v_pk_fma_f32 v[26:27], v[110:111], v[42:43], v[26:27] op_sel_hi:[1,0,1]
	v_pk_fma_f32 v[34:35], v[108:109], v[42:43], v[34:35] op_sel_hi:[1,0,1]
	v_pk_fma_f32 v[30:31], v[110:111], v[46:47], v[30:31] op_sel_hi:[1,0,1]
	v_pk_fma_f32 v[36:37], v[108:109], v[46:47], v[36:37] op_sel_hi:[1,0,1]
	global_load_dwordx4 v[108:111], v[50:51], off
	v_lshl_add_u64 v[50:51], v[50:51], 0, s[42:43]
	s_waitcnt vmcnt(23)
	v_pk_fma_f32 v[16:17], v[114:115], v[2:3], v[16:17] op_sel:[0,1,0]
	v_pk_fma_f32 v[20:21], v[112:113], v[2:3], v[20:21] op_sel:[0,1,0]
	v_pk_fma_f32 v[18:19], v[114:115], v[6:7], v[18:19] op_sel:[0,1,0]
	v_pk_fma_f32 v[28:29], v[112:113], v[6:7], v[28:29] op_sel:[0,1,0]
	v_pk_fma_f32 v[22:23], v[114:115], v[38:39], v[22:23] op_sel:[0,1,0]
	v_pk_fma_f32 v[32:33], v[112:113], v[38:39], v[32:33] op_sel:[0,1,0]
	v_pk_fma_f32 v[26:27], v[114:115], v[42:43], v[26:27] op_sel:[0,1,0]
	v_pk_fma_f32 v[34:35], v[112:113], v[42:43], v[34:35] op_sel:[0,1,0]
	v_pk_fma_f32 v[30:31], v[114:115], v[46:47], v[30:31] op_sel:[0,1,0]
	v_pk_fma_f32 v[36:37], v[112:113], v[46:47], v[36:37] op_sel:[0,1,0]
	global_load_dwordx4 v[112:115], v[50:51], off
	v_lshl_add_u64 v[50:51], v[50:51], 0, s[42:43]
	s_waitcnt vmcnt(23)
	v_pk_fma_f32 v[16:17], v[118:119], v[4:5], v[16:17] op_sel_hi:[1,0,1]
	v_pk_fma_f32 v[20:21], v[116:117], v[4:5], v[20:21] op_sel_hi:[1,0,1]
	v_pk_fma_f32 v[18:19], v[118:119], v[8:9], v[18:19] op_sel_hi:[1,0,1]
	v_pk_fma_f32 v[28:29], v[116:117], v[8:9], v[28:29] op_sel_hi:[1,0,1]
	v_pk_fma_f32 v[22:23], v[118:119], v[40:41], v[22:23] op_sel_hi:[1,0,1]
	v_pk_fma_f32 v[32:33], v[116:117], v[40:41], v[32:33] op_sel_hi:[1,0,1]
	v_pk_fma_f32 v[26:27], v[118:119], v[44:45], v[26:27] op_sel_hi:[1,0,1]
	v_pk_fma_f32 v[34:35], v[116:117], v[44:45], v[34:35] op_sel_hi:[1,0,1]
	v_pk_fma_f32 v[30:31], v[118:119], v[48:49], v[30:31] op_sel_hi:[1,0,1]
	v_pk_fma_f32 v[36:37], v[116:117], v[48:49], v[36:37] op_sel_hi:[1,0,1]
	global_load_dwordx4 v[116:119], v[50:51], off
	v_lshl_add_u64 v[50:51], v[50:51], 0, s[42:43]
	s_waitcnt vmcnt(23)
	v_pk_fma_f32 v[16:17], v[122:123], v[4:5], v[16:17] op_sel:[0,1,0]
	v_pk_fma_f32 v[20:21], v[120:121], v[4:5], v[20:21] op_sel:[0,1,0]
	v_pk_fma_f32 v[18:19], v[122:123], v[8:9], v[18:19] op_sel:[0,1,0]
	v_pk_fma_f32 v[28:29], v[120:121], v[8:9], v[28:29] op_sel:[0,1,0]
	v_pk_fma_f32 v[22:23], v[122:123], v[40:41], v[22:23] op_sel:[0,1,0]
	v_pk_fma_f32 v[32:33], v[120:121], v[40:41], v[32:33] op_sel:[0,1,0]
	v_pk_fma_f32 v[26:27], v[122:123], v[44:45], v[26:27] op_sel:[0,1,0]
	v_pk_fma_f32 v[34:35], v[120:121], v[44:45], v[34:35] op_sel:[0,1,0]
	v_pk_fma_f32 v[30:31], v[122:123], v[48:49], v[30:31] op_sel:[0,1,0]
	v_pk_fma_f32 v[36:37], v[120:121], v[48:49], v[36:37] op_sel:[0,1,0]
	global_load_dwordx4 v[120:123], v[50:51], off
	v_lshl_add_u64 v[50:51], v[50:51], 0, s[42:43]
	ds_read_b128 v[2:5], v54 offset:80
	ds_read_b128 v[6:9], v54 offset:4176
	ds_read_b128 v[38:41], v54 offset:8272
	ds_read_b128 v[42:45], v54 offset:12368
	ds_read_b128 v[46:49], v54 offset:16464
	s_waitcnt lgkmcnt(5)
	s_waitcnt vmcnt(23)
	v_pk_fma_f32 v[16:17], v[126:127], v[156:157], v[16:17] op_sel_hi:[1,0,1]
	v_pk_fma_f32 v[20:21], v[124:125], v[156:157], v[20:21] op_sel_hi:[1,0,1]
	v_pk_fma_f32 v[18:19], v[126:127], v[160:161], v[18:19] op_sel_hi:[1,0,1]
	v_pk_fma_f32 v[28:29], v[124:125], v[160:161], v[28:29] op_sel_hi:[1,0,1]
	v_pk_fma_f32 v[22:23], v[126:127], v[164:165], v[22:23] op_sel_hi:[1,0,1]
	v_pk_fma_f32 v[32:33], v[124:125], v[164:165], v[32:33] op_sel_hi:[1,0,1]
	v_pk_fma_f32 v[26:27], v[126:127], v[168:169], v[26:27] op_sel_hi:[1,0,1]
	v_pk_fma_f32 v[34:35], v[124:125], v[168:169], v[34:35] op_sel_hi:[1,0,1]
	v_pk_fma_f32 v[30:31], v[126:127], v[172:173], v[30:31] op_sel_hi:[1,0,1]
	v_pk_fma_f32 v[36:37], v[124:125], v[172:173], v[36:37] op_sel_hi:[1,0,1]
	global_load_dwordx4 v[124:127], v[50:51], off
	v_lshl_add_u64 v[50:51], v[50:51], 0, s[42:43]
	s_waitcnt vmcnt(23)
	v_pk_fma_f32 v[16:17], v[130:131], v[156:157], v[16:17] op_sel:[0,1,0]
	v_pk_fma_f32 v[20:21], v[128:129], v[156:157], v[20:21] op_sel:[0,1,0]
	v_pk_fma_f32 v[18:19], v[130:131], v[160:161], v[18:19] op_sel:[0,1,0]
	v_pk_fma_f32 v[28:29], v[128:129], v[160:161], v[28:29] op_sel:[0,1,0]
	v_pk_fma_f32 v[22:23], v[130:131], v[164:165], v[22:23] op_sel:[0,1,0]
	v_pk_fma_f32 v[32:33], v[128:129], v[164:165], v[32:33] op_sel:[0,1,0]
	v_pk_fma_f32 v[26:27], v[130:131], v[168:169], v[26:27] op_sel:[0,1,0]
	v_pk_fma_f32 v[34:35], v[128:129], v[168:169], v[34:35] op_sel:[0,1,0]
	v_pk_fma_f32 v[30:31], v[130:131], v[172:173], v[30:31] op_sel:[0,1,0]
	v_pk_fma_f32 v[36:37], v[128:129], v[172:173], v[36:37] op_sel:[0,1,0]
	global_load_dwordx4 v[128:131], v[50:51], off
	v_lshl_add_u64 v[50:51], v[50:51], 0, s[42:43]
	s_waitcnt vmcnt(23)
	v_pk_fma_f32 v[16:17], v[134:135], v[158:159], v[16:17] op_sel_hi:[1,0,1]
	v_pk_fma_f32 v[20:21], v[132:133], v[158:159], v[20:21] op_sel_hi:[1,0,1]
	v_pk_fma_f32 v[18:19], v[134:135], v[162:163], v[18:19] op_sel_hi:[1,0,1]
	v_pk_fma_f32 v[28:29], v[132:133], v[162:163], v[28:29] op_sel_hi:[1,0,1]
	v_pk_fma_f32 v[22:23], v[134:135], v[166:167], v[22:23] op_sel_hi:[1,0,1]
	v_pk_fma_f32 v[32:33], v[132:133], v[166:167], v[32:33] op_sel_hi:[1,0,1]
	v_pk_fma_f32 v[26:27], v[134:135], v[170:171], v[26:27] op_sel_hi:[1,0,1]
	v_pk_fma_f32 v[34:35], v[132:133], v[170:171], v[34:35] op_sel_hi:[1,0,1]
	v_pk_fma_f32 v[30:31], v[134:135], v[174:175], v[30:31] op_sel_hi:[1,0,1]
	v_pk_fma_f32 v[36:37], v[132:133], v[174:175], v[36:37] op_sel_hi:[1,0,1]
	global_load_dwordx4 v[132:135], v[50:51], off
	v_lshl_add_u64 v[50:51], v[50:51], 0, s[42:43]
	s_waitcnt vmcnt(23)
	v_pk_fma_f32 v[16:17], v[138:139], v[158:159], v[16:17] op_sel:[0,1,0]
	v_pk_fma_f32 v[20:21], v[136:137], v[158:159], v[20:21] op_sel:[0,1,0]
	v_pk_fma_f32 v[18:19], v[138:139], v[162:163], v[18:19] op_sel:[0,1,0]
	v_pk_fma_f32 v[28:29], v[136:137], v[162:163], v[28:29] op_sel:[0,1,0]
	v_pk_fma_f32 v[22:23], v[138:139], v[166:167], v[22:23] op_sel:[0,1,0]
	v_pk_fma_f32 v[32:33], v[136:137], v[166:167], v[32:33] op_sel:[0,1,0]
	v_pk_fma_f32 v[26:27], v[138:139], v[170:171], v[26:27] op_sel:[0,1,0]
	v_pk_fma_f32 v[34:35], v[136:137], v[170:171], v[34:35] op_sel:[0,1,0]
	v_pk_fma_f32 v[30:31], v[138:139], v[174:175], v[30:31] op_sel:[0,1,0]
	v_pk_fma_f32 v[36:37], v[136:137], v[174:175], v[36:37] op_sel:[0,1,0]
	global_load_dwordx4 v[136:139], v[50:51], off
	v_lshl_add_u64 v[50:51], v[50:51], 0, s[42:43]
	ds_read_b128 v[156:159], v54 offset:96
	ds_read_b128 v[160:163], v54 offset:4192
	ds_read_b128 v[164:167], v54 offset:8288
	ds_read_b128 v[168:171], v54 offset:12384
	ds_read_b128 v[172:175], v54 offset:16480
	s_waitcnt lgkmcnt(5)
	s_waitcnt vmcnt(23)
	v_pk_fma_f32 v[16:17], v[142:143], v[2:3], v[16:17] op_sel_hi:[1,0,1]
	v_pk_fma_f32 v[20:21], v[140:141], v[2:3], v[20:21] op_sel_hi:[1,0,1]
	v_pk_fma_f32 v[18:19], v[142:143], v[6:7], v[18:19] op_sel_hi:[1,0,1]
	v_pk_fma_f32 v[28:29], v[140:141], v[6:7], v[28:29] op_sel_hi:[1,0,1]
	v_pk_fma_f32 v[22:23], v[142:143], v[38:39], v[22:23] op_sel_hi:[1,0,1]
	v_pk_fma_f32 v[32:33], v[140:141], v[38:39], v[32:33] op_sel_hi:[1,0,1]
	v_pk_fma_f32 v[26:27], v[142:143], v[42:43], v[26:27] op_sel_hi:[1,0,1]
	v_pk_fma_f32 v[34:35], v[140:141], v[42:43], v[34:35] op_sel_hi:[1,0,1]
	v_pk_fma_f32 v[30:31], v[142:143], v[46:47], v[30:31] op_sel_hi:[1,0,1]
	v_pk_fma_f32 v[36:37], v[140:141], v[46:47], v[36:37] op_sel_hi:[1,0,1]
	global_load_dwordx4 v[140:143], v[50:51], off
	v_lshl_add_u64 v[50:51], v[50:51], 0, s[42:43]
	s_waitcnt vmcnt(23)
	v_pk_fma_f32 v[16:17], v[146:147], v[2:3], v[16:17] op_sel:[0,1,0]
	v_pk_fma_f32 v[20:21], v[144:145], v[2:3], v[20:21] op_sel:[0,1,0]
	v_pk_fma_f32 v[18:19], v[146:147], v[6:7], v[18:19] op_sel:[0,1,0]
	v_pk_fma_f32 v[28:29], v[144:145], v[6:7], v[28:29] op_sel:[0,1,0]
	v_pk_fma_f32 v[22:23], v[146:147], v[38:39], v[22:23] op_sel:[0,1,0]
	v_pk_fma_f32 v[32:33], v[144:145], v[38:39], v[32:33] op_sel:[0,1,0]
	v_pk_fma_f32 v[26:27], v[146:147], v[42:43], v[26:27] op_sel:[0,1,0]
	v_pk_fma_f32 v[34:35], v[144:145], v[42:43], v[34:35] op_sel:[0,1,0]
	v_pk_fma_f32 v[30:31], v[146:147], v[46:47], v[30:31] op_sel:[0,1,0]
	v_pk_fma_f32 v[36:37], v[144:145], v[46:47], v[36:37] op_sel:[0,1,0]
	global_load_dwordx4 v[144:147], v[50:51], off
	v_lshl_add_u64 v[50:51], v[50:51], 0, s[42:43]
	s_waitcnt vmcnt(23)
	v_pk_fma_f32 v[16:17], v[150:151], v[4:5], v[16:17] op_sel_hi:[1,0,1]
	v_pk_fma_f32 v[20:21], v[148:149], v[4:5], v[20:21] op_sel_hi:[1,0,1]
	v_pk_fma_f32 v[18:19], v[150:151], v[8:9], v[18:19] op_sel_hi:[1,0,1]
	v_pk_fma_f32 v[28:29], v[148:149], v[8:9], v[28:29] op_sel_hi:[1,0,1]
	v_pk_fma_f32 v[22:23], v[150:151], v[40:41], v[22:23] op_sel_hi:[1,0,1]
	v_pk_fma_f32 v[32:33], v[148:149], v[40:41], v[32:33] op_sel_hi:[1,0,1]
	v_pk_fma_f32 v[26:27], v[150:151], v[44:45], v[26:27] op_sel_hi:[1,0,1]
	v_pk_fma_f32 v[34:35], v[148:149], v[44:45], v[34:35] op_sel_hi:[1,0,1]
	v_pk_fma_f32 v[30:31], v[150:151], v[48:49], v[30:31] op_sel_hi:[1,0,1]
	v_pk_fma_f32 v[36:37], v[148:149], v[48:49], v[36:37] op_sel_hi:[1,0,1]
	global_load_dwordx4 v[148:151], v[50:51], off
	v_lshl_add_u64 v[50:51], v[50:51], 0, s[42:43]
	s_waitcnt vmcnt(23)
	v_pk_fma_f32 v[16:17], v[154:155], v[4:5], v[16:17] op_sel:[0,1,0]
	v_pk_fma_f32 v[20:21], v[152:153], v[4:5], v[20:21] op_sel:[0,1,0]
	v_pk_fma_f32 v[18:19], v[154:155], v[8:9], v[18:19] op_sel:[0,1,0]
	v_pk_fma_f32 v[28:29], v[152:153], v[8:9], v[28:29] op_sel:[0,1,0]
	v_pk_fma_f32 v[22:23], v[154:155], v[40:41], v[22:23] op_sel:[0,1,0]
	v_pk_fma_f32 v[32:33], v[152:153], v[40:41], v[32:33] op_sel:[0,1,0]
	v_pk_fma_f32 v[26:27], v[154:155], v[44:45], v[26:27] op_sel:[0,1,0]
	v_pk_fma_f32 v[34:35], v[152:153], v[44:45], v[34:35] op_sel:[0,1,0]
	v_pk_fma_f32 v[30:31], v[154:155], v[48:49], v[30:31] op_sel:[0,1,0]
	v_pk_fma_f32 v[36:37], v[152:153], v[48:49], v[36:37] op_sel:[0,1,0]
	global_load_dwordx4 v[152:155], v[50:51], off
	v_lshl_add_u64 v[50:51], v[50:51], 0, s[42:43]
	ds_read_b128 v[2:5], v54 offset:112
	ds_read_b128 v[6:9], v54 offset:4208
	ds_read_b128 v[38:41], v54 offset:8304
	ds_read_b128 v[42:45], v54 offset:12400
	ds_read_b128 v[46:49], v54 offset:16496
	s_waitcnt lgkmcnt(5)
	s_waitcnt vmcnt(23)
	v_pk_fma_f32 v[16:17], v[62:63], v[156:157], v[16:17] op_sel_hi:[1,0,1]
	v_pk_fma_f32 v[20:21], v[60:61], v[156:157], v[20:21] op_sel_hi:[1,0,1]
	v_pk_fma_f32 v[18:19], v[62:63], v[160:161], v[18:19] op_sel_hi:[1,0,1]
	v_pk_fma_f32 v[28:29], v[60:61], v[160:161], v[28:29] op_sel_hi:[1,0,1]
	v_pk_fma_f32 v[22:23], v[62:63], v[164:165], v[22:23] op_sel_hi:[1,0,1]
	v_pk_fma_f32 v[32:33], v[60:61], v[164:165], v[32:33] op_sel_hi:[1,0,1]
	v_pk_fma_f32 v[26:27], v[62:63], v[168:169], v[26:27] op_sel_hi:[1,0,1]
	v_pk_fma_f32 v[34:35], v[60:61], v[168:169], v[34:35] op_sel_hi:[1,0,1]
	v_pk_fma_f32 v[30:31], v[62:63], v[172:173], v[30:31] op_sel_hi:[1,0,1]
	v_pk_fma_f32 v[36:37], v[60:61], v[172:173], v[36:37] op_sel_hi:[1,0,1]
	global_load_dwordx4 v[60:63], v[50:51], off
	v_lshl_add_u64 v[50:51], v[50:51], 0, s[42:43]
	s_waitcnt vmcnt(23)
	v_pk_fma_f32 v[16:17], v[66:67], v[156:157], v[16:17] op_sel:[0,1,0]
	v_pk_fma_f32 v[20:21], v[64:65], v[156:157], v[20:21] op_sel:[0,1,0]
	v_pk_fma_f32 v[18:19], v[66:67], v[160:161], v[18:19] op_sel:[0,1,0]
	v_pk_fma_f32 v[28:29], v[64:65], v[160:161], v[28:29] op_sel:[0,1,0]
	v_pk_fma_f32 v[22:23], v[66:67], v[164:165], v[22:23] op_sel:[0,1,0]
	v_pk_fma_f32 v[32:33], v[64:65], v[164:165], v[32:33] op_sel:[0,1,0]
	v_pk_fma_f32 v[26:27], v[66:67], v[168:169], v[26:27] op_sel:[0,1,0]
	v_pk_fma_f32 v[34:35], v[64:65], v[168:169], v[34:35] op_sel:[0,1,0]
	v_pk_fma_f32 v[30:31], v[66:67], v[172:173], v[30:31] op_sel:[0,1,0]
	v_pk_fma_f32 v[36:37], v[64:65], v[172:173], v[36:37] op_sel:[0,1,0]
	global_load_dwordx4 v[64:67], v[50:51], off
	v_lshl_add_u64 v[50:51], v[50:51], 0, s[42:43]
	s_waitcnt vmcnt(23)
	v_pk_fma_f32 v[16:17], v[70:71], v[158:159], v[16:17] op_sel_hi:[1,0,1]
	v_pk_fma_f32 v[20:21], v[68:69], v[158:159], v[20:21] op_sel_hi:[1,0,1]
	v_pk_fma_f32 v[18:19], v[70:71], v[162:163], v[18:19] op_sel_hi:[1,0,1]
	v_pk_fma_f32 v[28:29], v[68:69], v[162:163], v[28:29] op_sel_hi:[1,0,1]
	v_pk_fma_f32 v[22:23], v[70:71], v[166:167], v[22:23] op_sel_hi:[1,0,1]
	v_pk_fma_f32 v[32:33], v[68:69], v[166:167], v[32:33] op_sel_hi:[1,0,1]
	v_pk_fma_f32 v[26:27], v[70:71], v[170:171], v[26:27] op_sel_hi:[1,0,1]
	v_pk_fma_f32 v[34:35], v[68:69], v[170:171], v[34:35] op_sel_hi:[1,0,1]
	v_pk_fma_f32 v[30:31], v[70:71], v[174:175], v[30:31] op_sel_hi:[1,0,1]
	v_pk_fma_f32 v[36:37], v[68:69], v[174:175], v[36:37] op_sel_hi:[1,0,1]
	global_load_dwordx4 v[68:71], v[50:51], off
	v_lshl_add_u64 v[50:51], v[50:51], 0, s[42:43]
	s_waitcnt vmcnt(23)
	v_pk_fma_f32 v[16:17], v[74:75], v[158:159], v[16:17] op_sel:[0,1,0]
	v_pk_fma_f32 v[20:21], v[72:73], v[158:159], v[20:21] op_sel:[0,1,0]
	v_pk_fma_f32 v[18:19], v[74:75], v[162:163], v[18:19] op_sel:[0,1,0]
	v_pk_fma_f32 v[28:29], v[72:73], v[162:163], v[28:29] op_sel:[0,1,0]
	v_pk_fma_f32 v[22:23], v[74:75], v[166:167], v[22:23] op_sel:[0,1,0]
	v_pk_fma_f32 v[32:33], v[72:73], v[166:167], v[32:33] op_sel:[0,1,0]
	v_pk_fma_f32 v[26:27], v[74:75], v[170:171], v[26:27] op_sel:[0,1,0]
	v_pk_fma_f32 v[34:35], v[72:73], v[170:171], v[34:35] op_sel:[0,1,0]
	v_pk_fma_f32 v[30:31], v[74:75], v[174:175], v[30:31] op_sel:[0,1,0]
	v_pk_fma_f32 v[36:37], v[72:73], v[174:175], v[36:37] op_sel:[0,1,0]
	global_load_dwordx4 v[72:75], v[50:51], off
	v_lshl_add_u64 v[50:51], v[50:51], 0, s[42:43]
	ds_read_b128 v[156:159], v54 offset:128
	ds_read_b128 v[160:163], v54 offset:4224
	ds_read_b128 v[164:167], v54 offset:8320
	ds_read_b128 v[168:171], v54 offset:12416
	ds_read_b128 v[172:175], v54 offset:16512
	s_waitcnt lgkmcnt(5)
	s_waitcnt vmcnt(23)
	v_pk_fma_f32 v[16:17], v[78:79], v[2:3], v[16:17] op_sel_hi:[1,0,1]
	v_pk_fma_f32 v[20:21], v[76:77], v[2:3], v[20:21] op_sel_hi:[1,0,1]
	v_pk_fma_f32 v[18:19], v[78:79], v[6:7], v[18:19] op_sel_hi:[1,0,1]
	v_pk_fma_f32 v[28:29], v[76:77], v[6:7], v[28:29] op_sel_hi:[1,0,1]
	v_pk_fma_f32 v[22:23], v[78:79], v[38:39], v[22:23] op_sel_hi:[1,0,1]
	v_pk_fma_f32 v[32:33], v[76:77], v[38:39], v[32:33] op_sel_hi:[1,0,1]
	v_pk_fma_f32 v[26:27], v[78:79], v[42:43], v[26:27] op_sel_hi:[1,0,1]
	v_pk_fma_f32 v[34:35], v[76:77], v[42:43], v[34:35] op_sel_hi:[1,0,1]
	v_pk_fma_f32 v[30:31], v[78:79], v[46:47], v[30:31] op_sel_hi:[1,0,1]
	v_pk_fma_f32 v[36:37], v[76:77], v[46:47], v[36:37] op_sel_hi:[1,0,1]
	global_load_dwordx4 v[76:79], v[50:51], off
	v_lshl_add_u64 v[50:51], v[50:51], 0, s[42:43]
	s_waitcnt vmcnt(23)
	v_pk_fma_f32 v[16:17], v[82:83], v[2:3], v[16:17] op_sel:[0,1,0]
	v_pk_fma_f32 v[20:21], v[80:81], v[2:3], v[20:21] op_sel:[0,1,0]
	v_pk_fma_f32 v[18:19], v[82:83], v[6:7], v[18:19] op_sel:[0,1,0]
	v_pk_fma_f32 v[28:29], v[80:81], v[6:7], v[28:29] op_sel:[0,1,0]
	v_pk_fma_f32 v[22:23], v[82:83], v[38:39], v[22:23] op_sel:[0,1,0]
	v_pk_fma_f32 v[32:33], v[80:81], v[38:39], v[32:33] op_sel:[0,1,0]
	v_pk_fma_f32 v[26:27], v[82:83], v[42:43], v[26:27] op_sel:[0,1,0]
	v_pk_fma_f32 v[34:35], v[80:81], v[42:43], v[34:35] op_sel:[0,1,0]
	v_pk_fma_f32 v[30:31], v[82:83], v[46:47], v[30:31] op_sel:[0,1,0]
	v_pk_fma_f32 v[36:37], v[80:81], v[46:47], v[36:37] op_sel:[0,1,0]
	global_load_dwordx4 v[80:83], v[50:51], off
	v_lshl_add_u64 v[50:51], v[50:51], 0, s[42:43]
	s_waitcnt vmcnt(23)
	v_pk_fma_f32 v[16:17], v[86:87], v[4:5], v[16:17] op_sel_hi:[1,0,1]
	v_pk_fma_f32 v[20:21], v[84:85], v[4:5], v[20:21] op_sel_hi:[1,0,1]
	v_pk_fma_f32 v[18:19], v[86:87], v[8:9], v[18:19] op_sel_hi:[1,0,1]
	v_pk_fma_f32 v[28:29], v[84:85], v[8:9], v[28:29] op_sel_hi:[1,0,1]
	v_pk_fma_f32 v[22:23], v[86:87], v[40:41], v[22:23] op_sel_hi:[1,0,1]
	v_pk_fma_f32 v[32:33], v[84:85], v[40:41], v[32:33] op_sel_hi:[1,0,1]
	v_pk_fma_f32 v[26:27], v[86:87], v[44:45], v[26:27] op_sel_hi:[1,0,1]
	v_pk_fma_f32 v[34:35], v[84:85], v[44:45], v[34:35] op_sel_hi:[1,0,1]
	v_pk_fma_f32 v[30:31], v[86:87], v[48:49], v[30:31] op_sel_hi:[1,0,1]
	v_pk_fma_f32 v[36:37], v[84:85], v[48:49], v[36:37] op_sel_hi:[1,0,1]
	global_load_dwordx4 v[84:87], v[50:51], off
	v_lshl_add_u64 v[50:51], v[50:51], 0, s[42:43]
	s_waitcnt vmcnt(23)
	v_pk_fma_f32 v[16:17], v[90:91], v[4:5], v[16:17] op_sel:[0,1,0]
	v_pk_fma_f32 v[20:21], v[88:89], v[4:5], v[20:21] op_sel:[0,1,0]
	v_pk_fma_f32 v[18:19], v[90:91], v[8:9], v[18:19] op_sel:[0,1,0]
	v_pk_fma_f32 v[28:29], v[88:89], v[8:9], v[28:29] op_sel:[0,1,0]
	v_pk_fma_f32 v[22:23], v[90:91], v[40:41], v[22:23] op_sel:[0,1,0]
	v_pk_fma_f32 v[32:33], v[88:89], v[40:41], v[32:33] op_sel:[0,1,0]
	v_pk_fma_f32 v[26:27], v[90:91], v[44:45], v[26:27] op_sel:[0,1,0]
	v_pk_fma_f32 v[34:35], v[88:89], v[44:45], v[34:35] op_sel:[0,1,0]
	v_pk_fma_f32 v[30:31], v[90:91], v[48:49], v[30:31] op_sel:[0,1,0]
	v_pk_fma_f32 v[36:37], v[88:89], v[48:49], v[36:37] op_sel:[0,1,0]
	global_load_dwordx4 v[88:91], v[50:51], off
	v_lshl_add_u64 v[50:51], v[50:51], 0, s[42:43]
	ds_read_b128 v[2:5], v54 offset:144
	ds_read_b128 v[6:9], v54 offset:4240
	ds_read_b128 v[38:41], v54 offset:8336
	ds_read_b128 v[42:45], v54 offset:12432
	ds_read_b128 v[46:49], v54 offset:16528
	s_waitcnt lgkmcnt(5)
	s_waitcnt vmcnt(23)
	v_pk_fma_f32 v[16:17], v[94:95], v[156:157], v[16:17] op_sel_hi:[1,0,1]
	v_pk_fma_f32 v[20:21], v[92:93], v[156:157], v[20:21] op_sel_hi:[1,0,1]
	v_pk_fma_f32 v[18:19], v[94:95], v[160:161], v[18:19] op_sel_hi:[1,0,1]
	v_pk_fma_f32 v[28:29], v[92:93], v[160:161], v[28:29] op_sel_hi:[1,0,1]
	v_pk_fma_f32 v[22:23], v[94:95], v[164:165], v[22:23] op_sel_hi:[1,0,1]
	v_pk_fma_f32 v[32:33], v[92:93], v[164:165], v[32:33] op_sel_hi:[1,0,1]
	v_pk_fma_f32 v[26:27], v[94:95], v[168:169], v[26:27] op_sel_hi:[1,0,1]
	v_pk_fma_f32 v[34:35], v[92:93], v[168:169], v[34:35] op_sel_hi:[1,0,1]
	v_pk_fma_f32 v[30:31], v[94:95], v[172:173], v[30:31] op_sel_hi:[1,0,1]
	v_pk_fma_f32 v[36:37], v[92:93], v[172:173], v[36:37] op_sel_hi:[1,0,1]
	global_load_dwordx4 v[92:95], v[50:51], off
	v_lshl_add_u64 v[50:51], v[50:51], 0, s[42:43]
	s_waitcnt vmcnt(23)
	v_pk_fma_f32 v[16:17], v[98:99], v[156:157], v[16:17] op_sel:[0,1,0]
	v_pk_fma_f32 v[20:21], v[96:97], v[156:157], v[20:21] op_sel:[0,1,0]
	v_pk_fma_f32 v[18:19], v[98:99], v[160:161], v[18:19] op_sel:[0,1,0]
	v_pk_fma_f32 v[28:29], v[96:97], v[160:161], v[28:29] op_sel:[0,1,0]
	v_pk_fma_f32 v[22:23], v[98:99], v[164:165], v[22:23] op_sel:[0,1,0]
	v_pk_fma_f32 v[32:33], v[96:97], v[164:165], v[32:33] op_sel:[0,1,0]
	v_pk_fma_f32 v[26:27], v[98:99], v[168:169], v[26:27] op_sel:[0,1,0]
	v_pk_fma_f32 v[34:35], v[96:97], v[168:169], v[34:35] op_sel:[0,1,0]
	v_pk_fma_f32 v[30:31], v[98:99], v[172:173], v[30:31] op_sel:[0,1,0]
	v_pk_fma_f32 v[36:37], v[96:97], v[172:173], v[36:37] op_sel:[0,1,0]
	global_load_dwordx4 v[96:99], v[50:51], off
	v_lshl_add_u64 v[50:51], v[50:51], 0, s[42:43]
	s_waitcnt vmcnt(23)
	v_pk_fma_f32 v[16:17], v[102:103], v[158:159], v[16:17] op_sel_hi:[1,0,1]
	v_pk_fma_f32 v[20:21], v[100:101], v[158:159], v[20:21] op_sel_hi:[1,0,1]
	v_pk_fma_f32 v[18:19], v[102:103], v[162:163], v[18:19] op_sel_hi:[1,0,1]
	v_pk_fma_f32 v[28:29], v[100:101], v[162:163], v[28:29] op_sel_hi:[1,0,1]
	v_pk_fma_f32 v[22:23], v[102:103], v[166:167], v[22:23] op_sel_hi:[1,0,1]
	v_pk_fma_f32 v[32:33], v[100:101], v[166:167], v[32:33] op_sel_hi:[1,0,1]
	v_pk_fma_f32 v[26:27], v[102:103], v[170:171], v[26:27] op_sel_hi:[1,0,1]
	v_pk_fma_f32 v[34:35], v[100:101], v[170:171], v[34:35] op_sel_hi:[1,0,1]
	v_pk_fma_f32 v[30:31], v[102:103], v[174:175], v[30:31] op_sel_hi:[1,0,1]
	v_pk_fma_f32 v[36:37], v[100:101], v[174:175], v[36:37] op_sel_hi:[1,0,1]
	global_load_dwordx4 v[100:103], v[50:51], off
	v_lshl_add_u64 v[50:51], v[50:51], 0, s[42:43]
	s_waitcnt vmcnt(23)
	v_pk_fma_f32 v[16:17], v[106:107], v[158:159], v[16:17] op_sel:[0,1,0]
	v_pk_fma_f32 v[20:21], v[104:105], v[158:159], v[20:21] op_sel:[0,1,0]
	v_pk_fma_f32 v[18:19], v[106:107], v[162:163], v[18:19] op_sel:[0,1,0]
	v_pk_fma_f32 v[28:29], v[104:105], v[162:163], v[28:29] op_sel:[0,1,0]
	v_pk_fma_f32 v[22:23], v[106:107], v[166:167], v[22:23] op_sel:[0,1,0]
	v_pk_fma_f32 v[32:33], v[104:105], v[166:167], v[32:33] op_sel:[0,1,0]
	v_pk_fma_f32 v[26:27], v[106:107], v[170:171], v[26:27] op_sel:[0,1,0]
	v_pk_fma_f32 v[34:35], v[104:105], v[170:171], v[34:35] op_sel:[0,1,0]
	v_pk_fma_f32 v[30:31], v[106:107], v[174:175], v[30:31] op_sel:[0,1,0]
	v_pk_fma_f32 v[36:37], v[104:105], v[174:175], v[36:37] op_sel:[0,1,0]
	global_load_dwordx4 v[104:107], v[50:51], off
	v_lshl_add_u64 v[50:51], v[50:51], 0, s[42:43]
	ds_read_b128 v[156:159], v54 offset:160
	ds_read_b128 v[160:163], v54 offset:4256
	ds_read_b128 v[164:167], v54 offset:8352
	ds_read_b128 v[168:171], v54 offset:12448
	ds_read_b128 v[172:175], v54 offset:16544
	s_waitcnt lgkmcnt(5)
	s_waitcnt vmcnt(23)
	v_pk_fma_f32 v[16:17], v[110:111], v[2:3], v[16:17] op_sel_hi:[1,0,1]
	v_pk_fma_f32 v[20:21], v[108:109], v[2:3], v[20:21] op_sel_hi:[1,0,1]
	v_pk_fma_f32 v[18:19], v[110:111], v[6:7], v[18:19] op_sel_hi:[1,0,1]
	v_pk_fma_f32 v[28:29], v[108:109], v[6:7], v[28:29] op_sel_hi:[1,0,1]
	v_pk_fma_f32 v[22:23], v[110:111], v[38:39], v[22:23] op_sel_hi:[1,0,1]
	v_pk_fma_f32 v[32:33], v[108:109], v[38:39], v[32:33] op_sel_hi:[1,0,1]
	v_pk_fma_f32 v[26:27], v[110:111], v[42:43], v[26:27] op_sel_hi:[1,0,1]
	v_pk_fma_f32 v[34:35], v[108:109], v[42:43], v[34:35] op_sel_hi:[1,0,1]
	v_pk_fma_f32 v[30:31], v[110:111], v[46:47], v[30:31] op_sel_hi:[1,0,1]
	v_pk_fma_f32 v[36:37], v[108:109], v[46:47], v[36:37] op_sel_hi:[1,0,1]
	global_load_dwordx4 v[108:111], v[50:51], off
	v_lshl_add_u64 v[50:51], v[50:51], 0, s[42:43]
	s_waitcnt vmcnt(23)
	v_pk_fma_f32 v[16:17], v[114:115], v[2:3], v[16:17] op_sel:[0,1,0]
	v_pk_fma_f32 v[20:21], v[112:113], v[2:3], v[20:21] op_sel:[0,1,0]
	v_pk_fma_f32 v[18:19], v[114:115], v[6:7], v[18:19] op_sel:[0,1,0]
	v_pk_fma_f32 v[28:29], v[112:113], v[6:7], v[28:29] op_sel:[0,1,0]
	v_pk_fma_f32 v[22:23], v[114:115], v[38:39], v[22:23] op_sel:[0,1,0]
	v_pk_fma_f32 v[32:33], v[112:113], v[38:39], v[32:33] op_sel:[0,1,0]
	v_pk_fma_f32 v[26:27], v[114:115], v[42:43], v[26:27] op_sel:[0,1,0]
	v_pk_fma_f32 v[34:35], v[112:113], v[42:43], v[34:35] op_sel:[0,1,0]
	v_pk_fma_f32 v[30:31], v[114:115], v[46:47], v[30:31] op_sel:[0,1,0]
	v_pk_fma_f32 v[36:37], v[112:113], v[46:47], v[36:37] op_sel:[0,1,0]
	global_load_dwordx4 v[112:115], v[50:51], off
	v_lshl_add_u64 v[50:51], v[50:51], 0, s[42:43]
	s_waitcnt vmcnt(23)
	v_pk_fma_f32 v[16:17], v[118:119], v[4:5], v[16:17] op_sel_hi:[1,0,1]
	v_pk_fma_f32 v[20:21], v[116:117], v[4:5], v[20:21] op_sel_hi:[1,0,1]
	v_pk_fma_f32 v[18:19], v[118:119], v[8:9], v[18:19] op_sel_hi:[1,0,1]
	v_pk_fma_f32 v[28:29], v[116:117], v[8:9], v[28:29] op_sel_hi:[1,0,1]
	v_pk_fma_f32 v[22:23], v[118:119], v[40:41], v[22:23] op_sel_hi:[1,0,1]
	v_pk_fma_f32 v[32:33], v[116:117], v[40:41], v[32:33] op_sel_hi:[1,0,1]
	v_pk_fma_f32 v[26:27], v[118:119], v[44:45], v[26:27] op_sel_hi:[1,0,1]
	v_pk_fma_f32 v[34:35], v[116:117], v[44:45], v[34:35] op_sel_hi:[1,0,1]
	v_pk_fma_f32 v[30:31], v[118:119], v[48:49], v[30:31] op_sel_hi:[1,0,1]
	v_pk_fma_f32 v[36:37], v[116:117], v[48:49], v[36:37] op_sel_hi:[1,0,1]
	global_load_dwordx4 v[116:119], v[50:51], off
	v_lshl_add_u64 v[50:51], v[50:51], 0, s[42:43]
	s_waitcnt vmcnt(23)
	v_pk_fma_f32 v[16:17], v[122:123], v[4:5], v[16:17] op_sel:[0,1,0]
	v_pk_fma_f32 v[20:21], v[120:121], v[4:5], v[20:21] op_sel:[0,1,0]
	v_pk_fma_f32 v[18:19], v[122:123], v[8:9], v[18:19] op_sel:[0,1,0]
	v_pk_fma_f32 v[28:29], v[120:121], v[8:9], v[28:29] op_sel:[0,1,0]
	v_pk_fma_f32 v[22:23], v[122:123], v[40:41], v[22:23] op_sel:[0,1,0]
	v_pk_fma_f32 v[32:33], v[120:121], v[40:41], v[32:33] op_sel:[0,1,0]
	v_pk_fma_f32 v[26:27], v[122:123], v[44:45], v[26:27] op_sel:[0,1,0]
	v_pk_fma_f32 v[34:35], v[120:121], v[44:45], v[34:35] op_sel:[0,1,0]
	v_pk_fma_f32 v[30:31], v[122:123], v[48:49], v[30:31] op_sel:[0,1,0]
	v_pk_fma_f32 v[36:37], v[120:121], v[48:49], v[36:37] op_sel:[0,1,0]
	global_load_dwordx4 v[120:123], v[50:51], off
	v_lshl_add_u64 v[50:51], v[50:51], 0, s[42:43]
	ds_read_b128 v[2:5], v54 offset:176
	ds_read_b128 v[6:9], v54 offset:4272
	ds_read_b128 v[38:41], v54 offset:8368
	ds_read_b128 v[42:45], v54 offset:12464
	ds_read_b128 v[46:49], v54 offset:16560
	s_waitcnt lgkmcnt(5)
	s_waitcnt vmcnt(23)
	v_pk_fma_f32 v[16:17], v[126:127], v[156:157], v[16:17] op_sel_hi:[1,0,1]
	v_pk_fma_f32 v[20:21], v[124:125], v[156:157], v[20:21] op_sel_hi:[1,0,1]
	v_pk_fma_f32 v[18:19], v[126:127], v[160:161], v[18:19] op_sel_hi:[1,0,1]
	v_pk_fma_f32 v[28:29], v[124:125], v[160:161], v[28:29] op_sel_hi:[1,0,1]
	v_pk_fma_f32 v[22:23], v[126:127], v[164:165], v[22:23] op_sel_hi:[1,0,1]
	v_pk_fma_f32 v[32:33], v[124:125], v[164:165], v[32:33] op_sel_hi:[1,0,1]
	v_pk_fma_f32 v[26:27], v[126:127], v[168:169], v[26:27] op_sel_hi:[1,0,1]
	v_pk_fma_f32 v[34:35], v[124:125], v[168:169], v[34:35] op_sel_hi:[1,0,1]
	v_pk_fma_f32 v[30:31], v[126:127], v[172:173], v[30:31] op_sel_hi:[1,0,1]
	v_pk_fma_f32 v[36:37], v[124:125], v[172:173], v[36:37] op_sel_hi:[1,0,1]
	s_waitcnt vmcnt(22)
	v_pk_fma_f32 v[16:17], v[130:131], v[156:157], v[16:17] op_sel:[0,1,0]
	v_pk_fma_f32 v[20:21], v[128:129], v[156:157], v[20:21] op_sel:[0,1,0]
	v_pk_fma_f32 v[18:19], v[130:131], v[160:161], v[18:19] op_sel:[0,1,0]
	v_pk_fma_f32 v[28:29], v[128:129], v[160:161], v[28:29] op_sel:[0,1,0]
	v_pk_fma_f32 v[22:23], v[130:131], v[164:165], v[22:23] op_sel:[0,1,0]
	v_pk_fma_f32 v[32:33], v[128:129], v[164:165], v[32:33] op_sel:[0,1,0]
	v_pk_fma_f32 v[26:27], v[130:131], v[168:169], v[26:27] op_sel:[0,1,0]
	v_pk_fma_f32 v[34:35], v[128:129], v[168:169], v[34:35] op_sel:[0,1,0]
	v_pk_fma_f32 v[30:31], v[130:131], v[172:173], v[30:31] op_sel:[0,1,0]
	v_pk_fma_f32 v[36:37], v[128:129], v[172:173], v[36:37] op_sel:[0,1,0]
	s_waitcnt vmcnt(21)
	v_pk_fma_f32 v[16:17], v[134:135], v[158:159], v[16:17] op_sel_hi:[1,0,1]
	v_pk_fma_f32 v[20:21], v[132:133], v[158:159], v[20:21] op_sel_hi:[1,0,1]
	v_pk_fma_f32 v[18:19], v[134:135], v[162:163], v[18:19] op_sel_hi:[1,0,1]
	v_pk_fma_f32 v[28:29], v[132:133], v[162:163], v[28:29] op_sel_hi:[1,0,1]
	v_pk_fma_f32 v[22:23], v[134:135], v[166:167], v[22:23] op_sel_hi:[1,0,1]
	v_pk_fma_f32 v[32:33], v[132:133], v[166:167], v[32:33] op_sel_hi:[1,0,1]
	v_pk_fma_f32 v[26:27], v[134:135], v[170:171], v[26:27] op_sel_hi:[1,0,1]
	v_pk_fma_f32 v[34:35], v[132:133], v[170:171], v[34:35] op_sel_hi:[1,0,1]
	v_pk_fma_f32 v[30:31], v[134:135], v[174:175], v[30:31] op_sel_hi:[1,0,1]
	v_pk_fma_f32 v[36:37], v[132:133], v[174:175], v[36:37] op_sel_hi:[1,0,1]
	s_waitcnt vmcnt(20)
	v_pk_fma_f32 v[16:17], v[138:139], v[158:159], v[16:17] op_sel:[0,1,0]
	v_pk_fma_f32 v[20:21], v[136:137], v[158:159], v[20:21] op_sel:[0,1,0]
	v_pk_fma_f32 v[18:19], v[138:139], v[162:163], v[18:19] op_sel:[0,1,0]
	v_pk_fma_f32 v[28:29], v[136:137], v[162:163], v[28:29] op_sel:[0,1,0]
	v_pk_fma_f32 v[22:23], v[138:139], v[166:167], v[22:23] op_sel:[0,1,0]
	v_pk_fma_f32 v[32:33], v[136:137], v[166:167], v[32:33] op_sel:[0,1,0]
	v_pk_fma_f32 v[26:27], v[138:139], v[170:171], v[26:27] op_sel:[0,1,0]
	v_pk_fma_f32 v[34:35], v[136:137], v[170:171], v[34:35] op_sel:[0,1,0]
	v_pk_fma_f32 v[30:31], v[138:139], v[174:175], v[30:31] op_sel:[0,1,0]
	v_pk_fma_f32 v[36:37], v[136:137], v[174:175], v[36:37] op_sel:[0,1,0]
	ds_read_b128 v[156:159], v54 offset:192
	ds_read_b128 v[160:163], v54 offset:4288
	ds_read_b128 v[164:167], v54 offset:8384
	ds_read_b128 v[168:171], v54 offset:12480
	ds_read_b128 v[172:175], v54 offset:16576
	s_waitcnt lgkmcnt(5)
	s_waitcnt vmcnt(19)
	v_pk_fma_f32 v[16:17], v[142:143], v[2:3], v[16:17] op_sel_hi:[1,0,1]
	v_pk_fma_f32 v[20:21], v[140:141], v[2:3], v[20:21] op_sel_hi:[1,0,1]
	v_pk_fma_f32 v[18:19], v[142:143], v[6:7], v[18:19] op_sel_hi:[1,0,1]
	v_pk_fma_f32 v[28:29], v[140:141], v[6:7], v[28:29] op_sel_hi:[1,0,1]
	v_pk_fma_f32 v[22:23], v[142:143], v[38:39], v[22:23] op_sel_hi:[1,0,1]
	v_pk_fma_f32 v[32:33], v[140:141], v[38:39], v[32:33] op_sel_hi:[1,0,1]
	v_pk_fma_f32 v[26:27], v[142:143], v[42:43], v[26:27] op_sel_hi:[1,0,1]
	v_pk_fma_f32 v[34:35], v[140:141], v[42:43], v[34:35] op_sel_hi:[1,0,1]
	v_pk_fma_f32 v[30:31], v[142:143], v[46:47], v[30:31] op_sel_hi:[1,0,1]
	v_pk_fma_f32 v[36:37], v[140:141], v[46:47], v[36:37] op_sel_hi:[1,0,1]
	s_waitcnt vmcnt(18)
	v_pk_fma_f32 v[16:17], v[146:147], v[2:3], v[16:17] op_sel:[0,1,0]
	v_pk_fma_f32 v[20:21], v[144:145], v[2:3], v[20:21] op_sel:[0,1,0]
	v_pk_fma_f32 v[18:19], v[146:147], v[6:7], v[18:19] op_sel:[0,1,0]
	v_pk_fma_f32 v[28:29], v[144:145], v[6:7], v[28:29] op_sel:[0,1,0]
	v_pk_fma_f32 v[22:23], v[146:147], v[38:39], v[22:23] op_sel:[0,1,0]
	v_pk_fma_f32 v[32:33], v[144:145], v[38:39], v[32:33] op_sel:[0,1,0]
	v_pk_fma_f32 v[26:27], v[146:147], v[42:43], v[26:27] op_sel:[0,1,0]
	v_pk_fma_f32 v[34:35], v[144:145], v[42:43], v[34:35] op_sel:[0,1,0]
	v_pk_fma_f32 v[30:31], v[146:147], v[46:47], v[30:31] op_sel:[0,1,0]
	v_pk_fma_f32 v[36:37], v[144:145], v[46:47], v[36:37] op_sel:[0,1,0]
	s_waitcnt vmcnt(17)
	v_pk_fma_f32 v[16:17], v[150:151], v[4:5], v[16:17] op_sel_hi:[1,0,1]
	v_pk_fma_f32 v[20:21], v[148:149], v[4:5], v[20:21] op_sel_hi:[1,0,1]
	v_pk_fma_f32 v[18:19], v[150:151], v[8:9], v[18:19] op_sel_hi:[1,0,1]
	v_pk_fma_f32 v[28:29], v[148:149], v[8:9], v[28:29] op_sel_hi:[1,0,1]
	v_pk_fma_f32 v[22:23], v[150:151], v[40:41], v[22:23] op_sel_hi:[1,0,1]
	v_pk_fma_f32 v[32:33], v[148:149], v[40:41], v[32:33] op_sel_hi:[1,0,1]
	v_pk_fma_f32 v[26:27], v[150:151], v[44:45], v[26:27] op_sel_hi:[1,0,1]
	v_pk_fma_f32 v[34:35], v[148:149], v[44:45], v[34:35] op_sel_hi:[1,0,1]
	v_pk_fma_f32 v[30:31], v[150:151], v[48:49], v[30:31] op_sel_hi:[1,0,1]
	v_pk_fma_f32 v[36:37], v[148:149], v[48:49], v[36:37] op_sel_hi:[1,0,1]
	s_waitcnt vmcnt(16)
	v_pk_fma_f32 v[16:17], v[154:155], v[4:5], v[16:17] op_sel:[0,1,0]
	v_pk_fma_f32 v[20:21], v[152:153], v[4:5], v[20:21] op_sel:[0,1,0]
	v_pk_fma_f32 v[18:19], v[154:155], v[8:9], v[18:19] op_sel:[0,1,0]
	v_pk_fma_f32 v[28:29], v[152:153], v[8:9], v[28:29] op_sel:[0,1,0]
	v_pk_fma_f32 v[22:23], v[154:155], v[40:41], v[22:23] op_sel:[0,1,0]
	v_pk_fma_f32 v[32:33], v[152:153], v[40:41], v[32:33] op_sel:[0,1,0]
	v_pk_fma_f32 v[26:27], v[154:155], v[44:45], v[26:27] op_sel:[0,1,0]
	v_pk_fma_f32 v[34:35], v[152:153], v[44:45], v[34:35] op_sel:[0,1,0]
	v_pk_fma_f32 v[30:31], v[154:155], v[48:49], v[30:31] op_sel:[0,1,0]
	v_pk_fma_f32 v[36:37], v[152:153], v[48:49], v[36:37] op_sel:[0,1,0]
	ds_read_b128 v[2:5], v54 offset:208
	ds_read_b128 v[6:9], v54 offset:4304
	ds_read_b128 v[38:41], v54 offset:8400
	ds_read_b128 v[42:45], v54 offset:12496
	ds_read_b128 v[46:49], v54 offset:16592
	s_waitcnt lgkmcnt(5)
	s_waitcnt vmcnt(15)
	v_pk_fma_f32 v[16:17], v[62:63], v[156:157], v[16:17] op_sel_hi:[1,0,1]
	v_pk_fma_f32 v[20:21], v[60:61], v[156:157], v[20:21] op_sel_hi:[1,0,1]
	v_pk_fma_f32 v[18:19], v[62:63], v[160:161], v[18:19] op_sel_hi:[1,0,1]
	v_pk_fma_f32 v[28:29], v[60:61], v[160:161], v[28:29] op_sel_hi:[1,0,1]
	v_pk_fma_f32 v[22:23], v[62:63], v[164:165], v[22:23] op_sel_hi:[1,0,1]
	v_pk_fma_f32 v[32:33], v[60:61], v[164:165], v[32:33] op_sel_hi:[1,0,1]
	v_pk_fma_f32 v[26:27], v[62:63], v[168:169], v[26:27] op_sel_hi:[1,0,1]
	v_pk_fma_f32 v[34:35], v[60:61], v[168:169], v[34:35] op_sel_hi:[1,0,1]
	v_pk_fma_f32 v[30:31], v[62:63], v[172:173], v[30:31] op_sel_hi:[1,0,1]
	v_pk_fma_f32 v[36:37], v[60:61], v[172:173], v[36:37] op_sel_hi:[1,0,1]
	s_waitcnt vmcnt(14)
	v_pk_fma_f32 v[16:17], v[66:67], v[156:157], v[16:17] op_sel:[0,1,0]
	v_pk_fma_f32 v[20:21], v[64:65], v[156:157], v[20:21] op_sel:[0,1,0]
	v_pk_fma_f32 v[18:19], v[66:67], v[160:161], v[18:19] op_sel:[0,1,0]
	v_pk_fma_f32 v[28:29], v[64:65], v[160:161], v[28:29] op_sel:[0,1,0]
	v_pk_fma_f32 v[22:23], v[66:67], v[164:165], v[22:23] op_sel:[0,1,0]
	v_pk_fma_f32 v[32:33], v[64:65], v[164:165], v[32:33] op_sel:[0,1,0]
	v_pk_fma_f32 v[26:27], v[66:67], v[168:169], v[26:27] op_sel:[0,1,0]
	v_pk_fma_f32 v[34:35], v[64:65], v[168:169], v[34:35] op_sel:[0,1,0]
	v_pk_fma_f32 v[30:31], v[66:67], v[172:173], v[30:31] op_sel:[0,1,0]
	v_pk_fma_f32 v[36:37], v[64:65], v[172:173], v[36:37] op_sel:[0,1,0]
	s_waitcnt vmcnt(13)
	v_pk_fma_f32 v[16:17], v[70:71], v[158:159], v[16:17] op_sel_hi:[1,0,1]
	v_pk_fma_f32 v[20:21], v[68:69], v[158:159], v[20:21] op_sel_hi:[1,0,1]
	v_pk_fma_f32 v[18:19], v[70:71], v[162:163], v[18:19] op_sel_hi:[1,0,1]
	v_pk_fma_f32 v[28:29], v[68:69], v[162:163], v[28:29] op_sel_hi:[1,0,1]
	v_pk_fma_f32 v[22:23], v[70:71], v[166:167], v[22:23] op_sel_hi:[1,0,1]
	v_pk_fma_f32 v[32:33], v[68:69], v[166:167], v[32:33] op_sel_hi:[1,0,1]
	v_pk_fma_f32 v[26:27], v[70:71], v[170:171], v[26:27] op_sel_hi:[1,0,1]
	v_pk_fma_f32 v[34:35], v[68:69], v[170:171], v[34:35] op_sel_hi:[1,0,1]
	v_pk_fma_f32 v[30:31], v[70:71], v[174:175], v[30:31] op_sel_hi:[1,0,1]
	v_pk_fma_f32 v[36:37], v[68:69], v[174:175], v[36:37] op_sel_hi:[1,0,1]
	s_waitcnt vmcnt(12)
	v_pk_fma_f32 v[16:17], v[74:75], v[158:159], v[16:17] op_sel:[0,1,0]
	v_pk_fma_f32 v[20:21], v[72:73], v[158:159], v[20:21] op_sel:[0,1,0]
	v_pk_fma_f32 v[18:19], v[74:75], v[162:163], v[18:19] op_sel:[0,1,0]
	v_pk_fma_f32 v[28:29], v[72:73], v[162:163], v[28:29] op_sel:[0,1,0]
	v_pk_fma_f32 v[22:23], v[74:75], v[166:167], v[22:23] op_sel:[0,1,0]
	v_pk_fma_f32 v[32:33], v[72:73], v[166:167], v[32:33] op_sel:[0,1,0]
	v_pk_fma_f32 v[26:27], v[74:75], v[170:171], v[26:27] op_sel:[0,1,0]
	v_pk_fma_f32 v[34:35], v[72:73], v[170:171], v[34:35] op_sel:[0,1,0]
	v_pk_fma_f32 v[30:31], v[74:75], v[174:175], v[30:31] op_sel:[0,1,0]
	v_pk_fma_f32 v[36:37], v[72:73], v[174:175], v[36:37] op_sel:[0,1,0]
	ds_read_b128 v[156:159], v54 offset:224
	ds_read_b128 v[160:163], v54 offset:4320
	ds_read_b128 v[164:167], v54 offset:8416
	ds_read_b128 v[168:171], v54 offset:12512
	ds_read_b128 v[172:175], v54 offset:16608
	s_waitcnt lgkmcnt(5)
	s_waitcnt vmcnt(11)
	v_pk_fma_f32 v[16:17], v[78:79], v[2:3], v[16:17] op_sel_hi:[1,0,1]
	v_pk_fma_f32 v[20:21], v[76:77], v[2:3], v[20:21] op_sel_hi:[1,0,1]
	v_pk_fma_f32 v[18:19], v[78:79], v[6:7], v[18:19] op_sel_hi:[1,0,1]
	v_pk_fma_f32 v[28:29], v[76:77], v[6:7], v[28:29] op_sel_hi:[1,0,1]
	v_pk_fma_f32 v[22:23], v[78:79], v[38:39], v[22:23] op_sel_hi:[1,0,1]
	v_pk_fma_f32 v[32:33], v[76:77], v[38:39], v[32:33] op_sel_hi:[1,0,1]
	v_pk_fma_f32 v[26:27], v[78:79], v[42:43], v[26:27] op_sel_hi:[1,0,1]
	v_pk_fma_f32 v[34:35], v[76:77], v[42:43], v[34:35] op_sel_hi:[1,0,1]
	v_pk_fma_f32 v[30:31], v[78:79], v[46:47], v[30:31] op_sel_hi:[1,0,1]
	v_pk_fma_f32 v[36:37], v[76:77], v[46:47], v[36:37] op_sel_hi:[1,0,1]
	s_waitcnt vmcnt(10)
	v_pk_fma_f32 v[16:17], v[82:83], v[2:3], v[16:17] op_sel:[0,1,0]
	v_pk_fma_f32 v[20:21], v[80:81], v[2:3], v[20:21] op_sel:[0,1,0]
	v_pk_fma_f32 v[18:19], v[82:83], v[6:7], v[18:19] op_sel:[0,1,0]
	v_pk_fma_f32 v[28:29], v[80:81], v[6:7], v[28:29] op_sel:[0,1,0]
	v_pk_fma_f32 v[22:23], v[82:83], v[38:39], v[22:23] op_sel:[0,1,0]
	v_pk_fma_f32 v[32:33], v[80:81], v[38:39], v[32:33] op_sel:[0,1,0]
	v_pk_fma_f32 v[26:27], v[82:83], v[42:43], v[26:27] op_sel:[0,1,0]
	v_pk_fma_f32 v[34:35], v[80:81], v[42:43], v[34:35] op_sel:[0,1,0]
	v_pk_fma_f32 v[30:31], v[82:83], v[46:47], v[30:31] op_sel:[0,1,0]
	v_pk_fma_f32 v[36:37], v[80:81], v[46:47], v[36:37] op_sel:[0,1,0]
	s_waitcnt vmcnt(9)
	v_pk_fma_f32 v[16:17], v[86:87], v[4:5], v[16:17] op_sel_hi:[1,0,1]
	v_pk_fma_f32 v[20:21], v[84:85], v[4:5], v[20:21] op_sel_hi:[1,0,1]
	v_pk_fma_f32 v[18:19], v[86:87], v[8:9], v[18:19] op_sel_hi:[1,0,1]
	v_pk_fma_f32 v[28:29], v[84:85], v[8:9], v[28:29] op_sel_hi:[1,0,1]
	v_pk_fma_f32 v[22:23], v[86:87], v[40:41], v[22:23] op_sel_hi:[1,0,1]
	v_pk_fma_f32 v[32:33], v[84:85], v[40:41], v[32:33] op_sel_hi:[1,0,1]
	v_pk_fma_f32 v[26:27], v[86:87], v[44:45], v[26:27] op_sel_hi:[1,0,1]
	v_pk_fma_f32 v[34:35], v[84:85], v[44:45], v[34:35] op_sel_hi:[1,0,1]
	v_pk_fma_f32 v[30:31], v[86:87], v[48:49], v[30:31] op_sel_hi:[1,0,1]
	v_pk_fma_f32 v[36:37], v[84:85], v[48:49], v[36:37] op_sel_hi:[1,0,1]
	s_waitcnt vmcnt(8)
	v_pk_fma_f32 v[16:17], v[90:91], v[4:5], v[16:17] op_sel:[0,1,0]
	v_pk_fma_f32 v[20:21], v[88:89], v[4:5], v[20:21] op_sel:[0,1,0]
	v_pk_fma_f32 v[18:19], v[90:91], v[8:9], v[18:19] op_sel:[0,1,0]
	v_pk_fma_f32 v[28:29], v[88:89], v[8:9], v[28:29] op_sel:[0,1,0]
	v_pk_fma_f32 v[22:23], v[90:91], v[40:41], v[22:23] op_sel:[0,1,0]
	v_pk_fma_f32 v[32:33], v[88:89], v[40:41], v[32:33] op_sel:[0,1,0]
	v_pk_fma_f32 v[26:27], v[90:91], v[44:45], v[26:27] op_sel:[0,1,0]
	v_pk_fma_f32 v[34:35], v[88:89], v[44:45], v[34:35] op_sel:[0,1,0]
	v_pk_fma_f32 v[30:31], v[90:91], v[48:49], v[30:31] op_sel:[0,1,0]
	v_pk_fma_f32 v[36:37], v[88:89], v[48:49], v[36:37] op_sel:[0,1,0]
	ds_read_b128 v[2:5], v54 offset:240
	ds_read_b128 v[6:9], v54 offset:4336
	ds_read_b128 v[38:41], v54 offset:8432
	ds_read_b128 v[42:45], v54 offset:12528
	ds_read_b128 v[46:49], v54 offset:16624
	s_waitcnt lgkmcnt(5)
	s_waitcnt vmcnt(7)
	v_pk_fma_f32 v[16:17], v[94:95], v[156:157], v[16:17] op_sel_hi:[1,0,1]
	v_pk_fma_f32 v[20:21], v[92:93], v[156:157], v[20:21] op_sel_hi:[1,0,1]
	v_pk_fma_f32 v[18:19], v[94:95], v[160:161], v[18:19] op_sel_hi:[1,0,1]
	v_pk_fma_f32 v[28:29], v[92:93], v[160:161], v[28:29] op_sel_hi:[1,0,1]
	v_pk_fma_f32 v[22:23], v[94:95], v[164:165], v[22:23] op_sel_hi:[1,0,1]
	v_pk_fma_f32 v[32:33], v[92:93], v[164:165], v[32:33] op_sel_hi:[1,0,1]
	v_pk_fma_f32 v[26:27], v[94:95], v[168:169], v[26:27] op_sel_hi:[1,0,1]
	v_pk_fma_f32 v[34:35], v[92:93], v[168:169], v[34:35] op_sel_hi:[1,0,1]
	v_pk_fma_f32 v[30:31], v[94:95], v[172:173], v[30:31] op_sel_hi:[1,0,1]
	v_pk_fma_f32 v[36:37], v[92:93], v[172:173], v[36:37] op_sel_hi:[1,0,1]
	s_waitcnt vmcnt(6)
	v_pk_fma_f32 v[16:17], v[98:99], v[156:157], v[16:17] op_sel:[0,1,0]
	v_pk_fma_f32 v[20:21], v[96:97], v[156:157], v[20:21] op_sel:[0,1,0]
	v_pk_fma_f32 v[18:19], v[98:99], v[160:161], v[18:19] op_sel:[0,1,0]
	v_pk_fma_f32 v[28:29], v[96:97], v[160:161], v[28:29] op_sel:[0,1,0]
	v_pk_fma_f32 v[22:23], v[98:99], v[164:165], v[22:23] op_sel:[0,1,0]
	v_pk_fma_f32 v[32:33], v[96:97], v[164:165], v[32:33] op_sel:[0,1,0]
	v_pk_fma_f32 v[26:27], v[98:99], v[168:169], v[26:27] op_sel:[0,1,0]
	v_pk_fma_f32 v[34:35], v[96:97], v[168:169], v[34:35] op_sel:[0,1,0]
	v_pk_fma_f32 v[30:31], v[98:99], v[172:173], v[30:31] op_sel:[0,1,0]
	v_pk_fma_f32 v[36:37], v[96:97], v[172:173], v[36:37] op_sel:[0,1,0]
	s_waitcnt vmcnt(5)
	v_pk_fma_f32 v[16:17], v[102:103], v[158:159], v[16:17] op_sel_hi:[1,0,1]
	v_pk_fma_f32 v[20:21], v[100:101], v[158:159], v[20:21] op_sel_hi:[1,0,1]
	v_pk_fma_f32 v[18:19], v[102:103], v[162:163], v[18:19] op_sel_hi:[1,0,1]
	v_pk_fma_f32 v[28:29], v[100:101], v[162:163], v[28:29] op_sel_hi:[1,0,1]
	v_pk_fma_f32 v[22:23], v[102:103], v[166:167], v[22:23] op_sel_hi:[1,0,1]
	v_pk_fma_f32 v[32:33], v[100:101], v[166:167], v[32:33] op_sel_hi:[1,0,1]
	v_pk_fma_f32 v[26:27], v[102:103], v[170:171], v[26:27] op_sel_hi:[1,0,1]
	v_pk_fma_f32 v[34:35], v[100:101], v[170:171], v[34:35] op_sel_hi:[1,0,1]
	v_pk_fma_f32 v[30:31], v[102:103], v[174:175], v[30:31] op_sel_hi:[1,0,1]
	v_pk_fma_f32 v[36:37], v[100:101], v[174:175], v[36:37] op_sel_hi:[1,0,1]
	s_waitcnt vmcnt(4)
	v_pk_fma_f32 v[16:17], v[106:107], v[158:159], v[16:17] op_sel:[0,1,0]
	v_pk_fma_f32 v[20:21], v[104:105], v[158:159], v[20:21] op_sel:[0,1,0]
	v_pk_fma_f32 v[18:19], v[106:107], v[162:163], v[18:19] op_sel:[0,1,0]
	v_pk_fma_f32 v[28:29], v[104:105], v[162:163], v[28:29] op_sel:[0,1,0]
	v_pk_fma_f32 v[22:23], v[106:107], v[166:167], v[22:23] op_sel:[0,1,0]
	v_pk_fma_f32 v[32:33], v[104:105], v[166:167], v[32:33] op_sel:[0,1,0]
	v_pk_fma_f32 v[26:27], v[106:107], v[170:171], v[26:27] op_sel:[0,1,0]
	v_pk_fma_f32 v[34:35], v[104:105], v[170:171], v[34:35] op_sel:[0,1,0]
	v_pk_fma_f32 v[30:31], v[106:107], v[174:175], v[30:31] op_sel:[0,1,0]
	v_pk_fma_f32 v[36:37], v[104:105], v[174:175], v[36:37] op_sel:[0,1,0]
	s_waitcnt lgkmcnt(0)
	s_waitcnt vmcnt(3)
	v_pk_fma_f32 v[16:17], v[110:111], v[2:3], v[16:17] op_sel_hi:[1,0,1]
	v_pk_fma_f32 v[20:21], v[108:109], v[2:3], v[20:21] op_sel_hi:[1,0,1]
	v_pk_fma_f32 v[18:19], v[110:111], v[6:7], v[18:19] op_sel_hi:[1,0,1]
	v_pk_fma_f32 v[28:29], v[108:109], v[6:7], v[28:29] op_sel_hi:[1,0,1]
	v_pk_fma_f32 v[22:23], v[110:111], v[38:39], v[22:23] op_sel_hi:[1,0,1]
	v_pk_fma_f32 v[32:33], v[108:109], v[38:39], v[32:33] op_sel_hi:[1,0,1]
	v_pk_fma_f32 v[26:27], v[110:111], v[42:43], v[26:27] op_sel_hi:[1,0,1]
	v_pk_fma_f32 v[34:35], v[108:109], v[42:43], v[34:35] op_sel_hi:[1,0,1]
	v_pk_fma_f32 v[30:31], v[110:111], v[46:47], v[30:31] op_sel_hi:[1,0,1]
	v_pk_fma_f32 v[36:37], v[108:109], v[46:47], v[36:37] op_sel_hi:[1,0,1]
	s_waitcnt vmcnt(2)
	v_pk_fma_f32 v[16:17], v[114:115], v[2:3], v[16:17] op_sel:[0,1,0]
	v_pk_fma_f32 v[20:21], v[112:113], v[2:3], v[20:21] op_sel:[0,1,0]
	v_pk_fma_f32 v[18:19], v[114:115], v[6:7], v[18:19] op_sel:[0,1,0]
	v_pk_fma_f32 v[28:29], v[112:113], v[6:7], v[28:29] op_sel:[0,1,0]
	v_pk_fma_f32 v[22:23], v[114:115], v[38:39], v[22:23] op_sel:[0,1,0]
	v_pk_fma_f32 v[32:33], v[112:113], v[38:39], v[32:33] op_sel:[0,1,0]
	v_pk_fma_f32 v[26:27], v[114:115], v[42:43], v[26:27] op_sel:[0,1,0]
	v_pk_fma_f32 v[34:35], v[112:113], v[42:43], v[34:35] op_sel:[0,1,0]
	v_pk_fma_f32 v[30:31], v[114:115], v[46:47], v[30:31] op_sel:[0,1,0]
	v_pk_fma_f32 v[36:37], v[112:113], v[46:47], v[36:37] op_sel:[0,1,0]
	s_waitcnt vmcnt(1)
	v_pk_fma_f32 v[16:17], v[118:119], v[4:5], v[16:17] op_sel_hi:[1,0,1]
	v_pk_fma_f32 v[20:21], v[116:117], v[4:5], v[20:21] op_sel_hi:[1,0,1]
	v_pk_fma_f32 v[18:19], v[118:119], v[8:9], v[18:19] op_sel_hi:[1,0,1]
	v_pk_fma_f32 v[28:29], v[116:117], v[8:9], v[28:29] op_sel_hi:[1,0,1]
	v_pk_fma_f32 v[22:23], v[118:119], v[40:41], v[22:23] op_sel_hi:[1,0,1]
	v_pk_fma_f32 v[32:33], v[116:117], v[40:41], v[32:33] op_sel_hi:[1,0,1]
	v_pk_fma_f32 v[26:27], v[118:119], v[44:45], v[26:27] op_sel_hi:[1,0,1]
	v_pk_fma_f32 v[34:35], v[116:117], v[44:45], v[34:35] op_sel_hi:[1,0,1]
	v_pk_fma_f32 v[30:31], v[118:119], v[48:49], v[30:31] op_sel_hi:[1,0,1]
	v_pk_fma_f32 v[36:37], v[116:117], v[48:49], v[36:37] op_sel_hi:[1,0,1]
	s_waitcnt vmcnt(0)
	v_pk_fma_f32 v[16:17], v[122:123], v[4:5], v[16:17] op_sel:[0,1,0]
	v_pk_fma_f32 v[20:21], v[120:121], v[4:5], v[20:21] op_sel:[0,1,0]
	v_pk_fma_f32 v[18:19], v[122:123], v[8:9], v[18:19] op_sel:[0,1,0]
	v_pk_fma_f32 v[28:29], v[120:121], v[8:9], v[28:29] op_sel:[0,1,0]
	v_pk_fma_f32 v[22:23], v[122:123], v[40:41], v[22:23] op_sel:[0,1,0]
	v_pk_fma_f32 v[32:33], v[120:121], v[40:41], v[32:33] op_sel:[0,1,0]
	v_pk_fma_f32 v[26:27], v[122:123], v[44:45], v[26:27] op_sel:[0,1,0]
	v_pk_fma_f32 v[34:35], v[120:121], v[44:45], v[34:35] op_sel:[0,1,0]
	v_pk_fma_f32 v[30:31], v[122:123], v[48:49], v[30:31] op_sel:[0,1,0]
	v_pk_fma_f32 v[36:37], v[120:121], v[48:49], v[36:37] op_sel:[0,1,0]
	v_cmp_eq_u32_e64 s[0:1], 0, v58
	s_and_saveexec_b64 s[18:19], s[0:1]
	s_cbranch_execz .LBB0_9
	v_mul_i32_i24_e32 v2, 0x2400, v57
	v_ashrrev_i32_e32 v3, 31, v2
	v_lshl_add_u64 v[2:3], v[2:3], 2, s[8:9]
	v_lshl_add_u64 v[2:3], v[14:15], 2, v[2:3]
	global_load_dwordx4 v[2:5], v[2:3], off
	s_waitcnt vmcnt(0)
	v_pk_add_f32 v[16:17], v[16:17], v[4:5]
	v_pk_add_f32 v[20:21], v[20:21], v[2:3]
	v_pk_add_f32 v[18:19], v[18:19], v[4:5]
	v_pk_add_f32 v[28:29], v[28:29], v[2:3]
	v_pk_add_f32 v[22:23], v[22:23], v[4:5]
	v_pk_add_f32 v[32:33], v[32:33], v[2:3]
	v_pk_add_f32 v[26:27], v[26:27], v[4:5]
	v_pk_add_f32 v[34:35], v[34:35], v[2:3]
	v_pk_add_f32 v[30:31], v[30:31], v[4:5]
	v_pk_add_f32 v[36:37], v[36:37], v[2:3]
	s_branch .LBB0_9
